# GDN prep 16x16 diagonal forward substitution re-scheduled: L-row LDS reads pipelined two deep instead of a full lgkmcnt(0) wait per row
# speedup vs baseline: 1.1486x; 1.0048x over previous
; DI void phase_gdn_prep(const Params& p, int l, char* smem) {
;     ...
;             if (tid < 128) {
;                 float* X = (tid < 64) ? sv : sk; const int col = tid & 63;
;                 float x[16];
; #pragma unroll
;                 for (int i = 0; i < 16; ++i) x[i] = X[(rb * 16 + i) * 65 + col];
; #pragma unroll
;                 for (int i = 1; i < 16; ++i) {
;                     const float* Lr = sL + (rb * 16 + i) * 64 + rb * 16;
;                     float acc = x[i];
; #pragma unroll
;                     for (int s2 = 0; s2 < i; ++s2) acc -= Lr[s2] * x[s2];
;                     x[i] = acc;
;                 }
; #pragma unroll
;                 for (int i = 1; i < 16; ++i) X[(rb * 16 + i) * 65 + col] = x[i];
;             }
.LBB0_339:
	s_and_saveexec_b64 s[86:87], s[48:49]
	s_cbranch_execz .LBB0_334
	s_mul_i32 s5, s4, 0x1040
	v_add_u32_e32 v191, s5, v77
	s_add_i32 s5, s5, 0xc300
	v_mov_b32_e32 v188, s5
	ds_read_b32 v192, v191
	ds_read_b32 v193, v191 offset:260
	ds_read_b32 v194, v191 offset:520
	ds_read_b32 v195, v191 offset:780
	ds_read_b32 v196, v191 offset:1040
	ds_read_b32 v197, v191 offset:1300
	ds_read_b32 v198, v191 offset:1560
	ds_read_b32 v199, v191 offset:1820
	ds_read_b32 v200, v191 offset:2080
	ds_read_b32 v201, v191 offset:2340
	ds_read_b32 v202, v191 offset:2600
	ds_read_b32 v203, v191 offset:2860
	ds_read_b32 v204, v191 offset:3120
	ds_read_b32 v205, v191 offset:3380
	ds_read_b32 v206, v191 offset:3640
	ds_read_b32 v207, v191 offset:3900
	ds_read_b128 v[36:39], v188 offset:256
	ds_read_b128 v[58:61], v188 offset:512
	s_waitcnt lgkmcnt(1)
	v_fma_f32 v193, -v192, v36, v193
	ds_read_b128 v[36:39], v188 offset:768
	s_waitcnt lgkmcnt(1)
	v_fma_f32 v194, -v192, v58, v194
	v_fma_f32 v194, -v193, v59, v194
	ds_read_b128 v[58:61], v188 offset:1024
	s_waitcnt lgkmcnt(1)
	v_fma_f32 v195, -v192, v36, v195
	v_fma_f32 v195, -v193, v37, v195
	v_fma_f32 v195, -v194, v38, v195
	ds_read_b128 v[36:39], v188 offset:1280
	s_waitcnt lgkmcnt(1)
	v_fma_f32 v196, -v192, v58, v196
	v_fma_f32 v196, -v193, v59, v196
	v_fma_f32 v196, -v194, v60, v196
	v_fma_f32 v196, -v195, v61, v196
	ds_read_b128 v[58:61], v188 offset:1536
	s_waitcnt lgkmcnt(1)
	v_fma_f32 v197, -v192, v36, v197
	v_fma_f32 v197, -v193, v37, v197
	v_fma_f32 v197, -v194, v38, v197
	v_fma_f32 v197, -v195, v39, v197
	ds_read_b128 v[36:39], v188 offset:1792
	s_waitcnt lgkmcnt(1)
	v_fma_f32 v198, -v192, v58, v198
	v_fma_f32 v198, -v193, v59, v198
	v_fma_f32 v198, -v194, v60, v198
	v_fma_f32 v198, -v195, v61, v198
	ds_read_b128 v[58:61], v188 offset:2048
	s_waitcnt lgkmcnt(1)
	v_fma_f32 v199, -v192, v36, v199
	v_fma_f32 v199, -v193, v37, v199
	v_fma_f32 v199, -v194, v38, v199
	v_fma_f32 v199, -v195, v39, v199
	ds_read_b128 v[36:39], v188 offset:2304
	s_waitcnt lgkmcnt(1)
	v_fma_f32 v200, -v192, v58, v200
	v_fma_f32 v200, -v193, v59, v200
	v_fma_f32 v200, -v194, v60, v200
	v_fma_f32 v200, -v195, v61, v200
	ds_read_b128 v[58:61], v188 offset:2560
	s_waitcnt lgkmcnt(1)
	v_fma_f32 v201, -v192, v36, v201
	v_fma_f32 v201, -v193, v37, v201
	v_fma_f32 v201, -v194, v38, v201
	v_fma_f32 v201, -v195, v39, v201
	ds_read_b128 v[36:39], v188 offset:2816
	s_waitcnt lgkmcnt(1)
	v_fma_f32 v202, -v192, v58, v202
	v_fma_f32 v202, -v193, v59, v202
	v_fma_f32 v202, -v194, v60, v202
	v_fma_f32 v202, -v195, v61, v202
	ds_read_b128 v[58:61], v188 offset:3072
	s_waitcnt lgkmcnt(1)
	v_fma_f32 v203, -v192, v36, v203
	v_fma_f32 v203, -v193, v37, v203
	v_fma_f32 v203, -v194, v38, v203
	v_fma_f32 v203, -v195, v39, v203
	ds_read_b128 v[36:39], v188 offset:3328
	s_waitcnt lgkmcnt(1)
	v_fma_f32 v204, -v192, v58, v204
	v_fma_f32 v204, -v193, v59, v204
	v_fma_f32 v204, -v194, v60, v204
	v_fma_f32 v204, -v195, v61, v204
	ds_read_b128 v[58:61], v188 offset:3584
	s_waitcnt lgkmcnt(1)
	v_fma_f32 v205, -v192, v36, v205
	v_fma_f32 v205, -v193, v37, v205
	v_fma_f32 v205, -v194, v38, v205
	v_fma_f32 v205, -v195, v39, v205
	ds_read_b128 v[36:39], v188 offset:3840
	s_waitcnt lgkmcnt(1)
	v_fma_f32 v206, -v192, v58, v206
	v_fma_f32 v206, -v193, v59, v206
	v_fma_f32 v206, -v194, v60, v206
	v_fma_f32 v206, -v195, v61, v206
	ds_read_b128 v[58:61], v188 offset:1296
	s_waitcnt lgkmcnt(1)
	v_fma_f32 v207, -v192, v36, v207
	v_fma_f32 v207, -v193, v37, v207
	v_fma_f32 v207, -v194, v38, v207
	v_fma_f32 v207, -v195, v39, v207
	ds_read_b128 v[36:39], v188 offset:1552
	s_waitcnt lgkmcnt(1)
	v_fma_f32 v197, -v196, v58, v197
	ds_read_b128 v[58:61], v188 offset:1808
	s_waitcnt lgkmcnt(1)
	v_fma_f32 v198, -v196, v36, v198
	v_fma_f32 v198, -v197, v37, v198
	ds_read_b128 v[36:39], v188 offset:2064
	s_waitcnt lgkmcnt(1)
; DI void phase_gdn_prep(const Params& p, int l, char* smem) {
;     ...
; #pragma unroll
;                 for (int i = 1; i < 16; ++i) {
;                     const float* Lr = sL + (rb * 16 + i) * 64 + rb * 16;
;                     float acc = x[i];
; #pragma unroll
;                     for (int s2 = 0; s2 < i; ++s2) acc -= Lr[s2] * x[s2];
;                     x[i] = acc;
;                 }
; #pragma unroll
;                 for (int i = 1; i < 16; ++i) X[(rb * 16 + i) * 65 + col] = x[i];
	v_fma_f32 v199, -v196, v58, v199
	v_fma_f32 v199, -v197, v59, v199
	v_fma_f32 v199, -v198, v60, v199
	ds_read_b128 v[58:61], v188 offset:2320
	s_waitcnt lgkmcnt(1)
	v_fma_f32 v200, -v196, v36, v200
	v_fma_f32 v200, -v197, v37, v200
	v_fma_f32 v200, -v198, v38, v200
	v_fma_f32 v200, -v199, v39, v200
	ds_read_b128 v[36:39], v188 offset:2576
	s_waitcnt lgkmcnt(1)
	v_fma_f32 v201, -v196, v58, v201
	v_fma_f32 v201, -v197, v59, v201
	v_fma_f32 v201, -v198, v60, v201
	v_fma_f32 v201, -v199, v61, v201
	ds_read_b128 v[58:61], v188 offset:2832
	s_waitcnt lgkmcnt(1)
	v_fma_f32 v202, -v196, v36, v202
	v_fma_f32 v202, -v197, v37, v202
	v_fma_f32 v202, -v198, v38, v202
	v_fma_f32 v202, -v199, v39, v202
	ds_read_b128 v[36:39], v188 offset:3088
	s_waitcnt lgkmcnt(1)
	v_fma_f32 v203, -v196, v58, v203
	v_fma_f32 v203, -v197, v59, v203
	v_fma_f32 v203, -v198, v60, v203
	v_fma_f32 v203, -v199, v61, v203
	ds_read_b128 v[58:61], v188 offset:3344
	s_waitcnt lgkmcnt(1)
	v_fma_f32 v204, -v196, v36, v204
	v_fma_f32 v204, -v197, v37, v204
	v_fma_f32 v204, -v198, v38, v204
	v_fma_f32 v204, -v199, v39, v204
	ds_read_b128 v[36:39], v188 offset:3600
	s_waitcnt lgkmcnt(1)
	v_fma_f32 v205, -v196, v58, v205
	v_fma_f32 v205, -v197, v59, v205
	v_fma_f32 v205, -v198, v60, v205
	v_fma_f32 v205, -v199, v61, v205
	ds_read_b128 v[58:61], v188 offset:3856
	s_waitcnt lgkmcnt(1)
	v_fma_f32 v206, -v196, v36, v206
	v_fma_f32 v206, -v197, v37, v206
	v_fma_f32 v206, -v198, v38, v206
	v_fma_f32 v206, -v199, v39, v206
	ds_read_b128 v[36:39], v188 offset:2336
	s_waitcnt lgkmcnt(1)
	v_fma_f32 v207, -v196, v58, v207
	v_fma_f32 v207, -v197, v59, v207
	v_fma_f32 v207, -v198, v60, v207
	v_fma_f32 v207, -v199, v61, v207
	ds_read_b128 v[58:61], v188 offset:2592
	s_waitcnt lgkmcnt(1)
	v_fma_f32 v201, -v200, v36, v201
	ds_read_b128 v[36:39], v188 offset:2848
	s_waitcnt lgkmcnt(1)
	v_fma_f32 v202, -v200, v58, v202
	v_fma_f32 v202, -v201, v59, v202
	ds_read_b128 v[58:61], v188 offset:3104
	s_waitcnt lgkmcnt(1)
	v_fma_f32 v203, -v200, v36, v203
	v_fma_f32 v203, -v201, v37, v203
	v_fma_f32 v203, -v202, v38, v203
	ds_read_b128 v[36:39], v188 offset:3360
	s_waitcnt lgkmcnt(1)
	v_fma_f32 v204, -v200, v58, v204
	v_fma_f32 v204, -v201, v59, v204
	v_fma_f32 v204, -v202, v60, v204
	v_fma_f32 v204, -v203, v61, v204
	ds_read_b128 v[58:61], v188 offset:3616
	s_waitcnt lgkmcnt(1)
	v_fma_f32 v205, -v200, v36, v205
	v_fma_f32 v205, -v201, v37, v205
	v_fma_f32 v205, -v202, v38, v205
	v_fma_f32 v205, -v203, v39, v205
	ds_read_b128 v[36:39], v188 offset:3872
	s_waitcnt lgkmcnt(1)
	v_fma_f32 v206, -v200, v58, v206
	v_fma_f32 v206, -v201, v59, v206
	v_fma_f32 v206, -v202, v60, v206
	v_fma_f32 v206, -v203, v61, v206
	ds_read_b128 v[58:61], v188 offset:3376
	s_waitcnt lgkmcnt(1)
	v_fma_f32 v207, -v200, v36, v207
	v_fma_f32 v207, -v201, v37, v207
	v_fma_f32 v207, -v202, v38, v207
	v_fma_f32 v207, -v203, v39, v207
	ds_read_b128 v[36:39], v188 offset:3632
	s_waitcnt lgkmcnt(1)
	v_fma_f32 v205, -v204, v58, v205
	ds_read_b128 v[58:61], v188 offset:3888
	s_waitcnt lgkmcnt(1)
	v_fma_f32 v206, -v204, v36, v206
	v_fma_f32 v206, -v205, v37, v206
	s_waitcnt lgkmcnt(0)
	v_fma_f32 v207, -v204, v58, v207
	v_fma_f32 v207, -v205, v59, v207
	v_fma_f32 v207, -v206, v60, v207
	ds_write_b32 v191, v193 offset:260
	ds_write_b32 v191, v194 offset:520
	ds_write_b32 v191, v195 offset:780
	ds_write_b32 v191, v196 offset:1040
	ds_write_b32 v191, v197 offset:1300
	ds_write_b32 v191, v198 offset:1560
	ds_write_b32 v191, v199 offset:1820
	ds_write_b32 v191, v200 offset:2080
	ds_write_b32 v191, v201 offset:2340
	ds_write_b32 v191, v202 offset:2600
	ds_write_b32 v191, v203 offset:2860
	ds_write_b32 v191, v204 offset:3120
	ds_write_b32 v191, v205 offset:3380
	ds_write_b32 v191, v206 offset:3640
	ds_write_b32 v191, v207 offset:3900
	s_branch .LBB0_334
